# P6 epilogue: hoisted residual loads + lane-permuted 64B-contiguous nt stores
# baseline (speedup 1.0000x reference)
.LBB0_1471:
	v_lshl_add_u32 v146, s18, 8, v148
	v_lshl_or_b32 v144, s42, 8, v150
	v_ashrrev_i32_e32 v147, 31, v146
	v_ashrrev_i32_e32 v145, 31, v144
	v_lshlrev_b64 v[242:243], 11, v[146:147]
	s_mov_b64 s[52:53], 0x10000
	s_mov_b64 s[54:55], 0x50000
	v_lshl_add_u64 v[242:243], v[242:243], 0, v[144:145]
	s_mov_b64 s[56:57], 0x20000
	s_mov_b64 s[58:59], 0xa0000
	v_mbcnt_lo_u32_b32 v252, -1, 0
	v_mbcnt_hi_u32_b32 v252, -1, v252
	v_and_b32_e32 v252, 48, v252
	v_readlane_b32 s44, v254, 16
	v_readlane_b32 s48, v254, 20
	v_readlane_b32 s49, v254, 21
	s_mov_b64 s[20:21], s[48:49]
	s_andn2_b64 vcc, exec, s[0:1]
	s_mov_b64 s[0:1], -1
	v_readlane_b32 s45, v254, 17
	v_readlane_b32 s46, v254, 18
	v_readlane_b32 s47, v254, 19
	v_readlane_b32 s50, v254, 22
	v_readlane_b32 s51, v254, 23
	v_lshl_add_u64 v[230:231], v[242:243], 1, s[4:5]
	global_load_dwordx4 v[166:169], v[230:231], off nt
	global_load_dwordx4 v[170:173], v[230:231], off offset:256 nt
	v_lshl_add_u64 v[230:231], v[230:231], 0, s[52:53]
	global_load_dwordx4 v[174:177], v[230:231], off nt
	global_load_dwordx4 v[178:181], v[230:231], off offset:256 nt
	v_lshl_add_u64 v[230:231], v[230:231], 0, s[52:53]
	global_load_dwordx4 v[182:185], v[230:231], off nt
	global_load_dwordx4 v[186:189], v[230:231], off offset:256 nt
	v_lshl_add_u64 v[230:231], v[230:231], 0, s[52:53]
	global_load_dwordx4 v[190:193], v[230:231], off nt
	global_load_dwordx4 v[194:197], v[230:231], off offset:256 nt
	v_lshl_add_u64 v[230:231], v[230:231], 0, s[54:55]
	global_load_dwordx4 v[198:201], v[230:231], off nt
	global_load_dwordx4 v[202:205], v[230:231], off offset:256 nt
	v_lshl_add_u64 v[230:231], v[230:231], 0, s[52:53]
	global_load_dwordx4 v[206:209], v[230:231], off nt
	global_load_dwordx4 v[210:213], v[230:231], off offset:256 nt
	v_lshl_add_u64 v[230:231], v[230:231], 0, s[52:53]
	global_load_dwordx4 v[214:217], v[230:231], off nt
	global_load_dwordx4 v[218:221], v[230:231], off offset:256 nt
	v_lshl_add_u64 v[230:231], v[230:231], 0, s[52:53]
	global_load_dwordx4 v[222:225], v[230:231], off nt
	global_load_dwordx4 v[226:229], v[230:231], off offset:256 nt
	v_lshl_add_u64 v[232:233], v[242:243], 2, s[20:21]
	v_sub_u32_e32 v232, v232, v252
	s_waitcnt vmcnt(15)
	v_lshlrev_b32_e32 v234, 16, v166
	v_and_b32_e32 v235, 0xffff0000, v166
	v_lshlrev_b32_e32 v236, 16, v167
	v_and_b32_e32 v237, 0xffff0000, v167
	v_lshlrev_b32_e32 v238, 16, v168
	v_and_b32_e32 v239, 0xffff0000, v168
	v_lshlrev_b32_e32 v240, 16, v169
	v_and_b32_e32 v241, 0xffff0000, v169
	v_pk_add_f32 v[234:235], v[124:125], v[234:235]
	v_pk_add_f32 v[238:239], v[120:121], v[238:239]
	v_pk_add_f32 v[236:237], v[126:127], v[236:237]
	v_pk_add_f32 v[240:241], v[122:123], v[240:241]
	s_nop 1
	v_permlane16_swap_b32_e32 v234, v238
	v_permlane16_swap_b32_e32 v235, v239
	v_permlane16_swap_b32_e32 v236, v240
	v_permlane16_swap_b32_e32 v237, v241
	v_permlane32_swap_b32_e32 v234, v238
	v_permlane32_swap_b32_e32 v235, v239
	v_permlane32_swap_b32_e32 v236, v240
	v_permlane32_swap_b32_e32 v237, v241
	global_store_dwordx4 v[232:233], v[234:237], off nt
	global_store_dwordx4 v[232:233], v[238:241], off offset:64 nt
	s_waitcnt vmcnt(16)
	v_lshlrev_b32_e32 v244, 16, v170
	v_and_b32_e32 v245, 0xffff0000, v170
	v_lshlrev_b32_e32 v246, 16, v171
	v_and_b32_e32 v247, 0xffff0000, v171
	v_lshlrev_b32_e32 v248, 16, v172
	v_and_b32_e32 v249, 0xffff0000, v172
	v_lshlrev_b32_e32 v250, 16, v173
	v_and_b32_e32 v251, 0xffff0000, v173
	v_pk_add_f32 v[244:245], v[116:117], v[244:245]
	v_pk_add_f32 v[248:249], v[112:113], v[248:249]
	v_pk_add_f32 v[246:247], v[118:119], v[246:247]
	v_pk_add_f32 v[250:251], v[114:115], v[250:251]
	s_nop 1
	v_permlane16_swap_b32_e32 v244, v248
	v_permlane16_swap_b32_e32 v245, v249
	v_permlane16_swap_b32_e32 v246, v250
	v_permlane16_swap_b32_e32 v247, v251
	v_permlane32_swap_b32_e32 v244, v248
	v_permlane32_swap_b32_e32 v245, v249
	v_permlane32_swap_b32_e32 v246, v250
	v_permlane32_swap_b32_e32 v247, v251
	global_store_dwordx4 v[232:233], v[244:247], off offset:512 nt
	global_store_dwordx4 v[232:233], v[248:251], off offset:576 nt
	v_lshl_add_u64 v[232:233], v[232:233], 0, s[56:57]
	s_waitcnt vmcnt(17)
	v_lshlrev_b32_e32 v234, 16, v174
	v_and_b32_e32 v235, 0xffff0000, v174
	v_lshlrev_b32_e32 v236, 16, v175
	v_and_b32_e32 v237, 0xffff0000, v175
	v_lshlrev_b32_e32 v238, 16, v176
	v_and_b32_e32 v239, 0xffff0000, v176
	v_lshlrev_b32_e32 v240, 16, v177
	v_and_b32_e32 v241, 0xffff0000, v177
	v_pk_add_f32 v[234:235], v[108:109], v[234:235]
	v_pk_add_f32 v[238:239], v[104:105], v[238:239]
	v_pk_add_f32 v[236:237], v[110:111], v[236:237]
	v_pk_add_f32 v[240:241], v[106:107], v[240:241]
	s_nop 1
	v_permlane16_swap_b32_e32 v234, v238
	v_permlane16_swap_b32_e32 v235, v239
	v_permlane16_swap_b32_e32 v236, v240
	v_permlane16_swap_b32_e32 v237, v241
	v_permlane32_swap_b32_e32 v234, v238
	v_permlane32_swap_b32_e32 v235, v239
	v_permlane32_swap_b32_e32 v236, v240
	v_permlane32_swap_b32_e32 v237, v241
	global_store_dwordx4 v[232:233], v[234:237], off nt
	global_store_dwordx4 v[232:233], v[238:241], off offset:64 nt
	s_waitcnt vmcnt(18)
	v_lshlrev_b32_e32 v244, 16, v178
	v_and_b32_e32 v245, 0xffff0000, v178
	v_lshlrev_b32_e32 v246, 16, v179
	v_and_b32_e32 v247, 0xffff0000, v179
	v_lshlrev_b32_e32 v248, 16, v180
	v_and_b32_e32 v249, 0xffff0000, v180
	v_lshlrev_b32_e32 v250, 16, v181
	v_and_b32_e32 v251, 0xffff0000, v181
	v_pk_add_f32 v[244:245], v[100:101], v[244:245]
	v_pk_add_f32 v[248:249], v[96:97], v[248:249]
	v_pk_add_f32 v[246:247], v[102:103], v[246:247]
	v_pk_add_f32 v[250:251], v[98:99], v[250:251]
	s_nop 1
	v_permlane16_swap_b32_e32 v244, v248
	v_permlane16_swap_b32_e32 v245, v249
	v_permlane16_swap_b32_e32 v246, v250
	v_permlane16_swap_b32_e32 v247, v251
	v_permlane32_swap_b32_e32 v244, v248
	v_permlane32_swap_b32_e32 v245, v249
	v_permlane32_swap_b32_e32 v246, v250
	v_permlane32_swap_b32_e32 v247, v251
	global_store_dwordx4 v[232:233], v[244:247], off offset:512 nt
	global_store_dwordx4 v[232:233], v[248:251], off offset:576 nt
	v_lshl_add_u64 v[232:233], v[232:233], 0, s[56:57]
	s_waitcnt vmcnt(19)
	v_lshlrev_b32_e32 v234, 16, v182
	v_and_b32_e32 v235, 0xffff0000, v182
	v_lshlrev_b32_e32 v236, 16, v183
	v_and_b32_e32 v237, 0xffff0000, v183
	v_lshlrev_b32_e32 v238, 16, v184
	v_and_b32_e32 v239, 0xffff0000, v184
	v_lshlrev_b32_e32 v240, 16, v185
	v_and_b32_e32 v241, 0xffff0000, v185
	v_pk_add_f32 v[234:235], v[92:93], v[234:235]
	v_pk_add_f32 v[238:239], v[88:89], v[238:239]
	v_pk_add_f32 v[236:237], v[94:95], v[236:237]
	v_pk_add_f32 v[240:241], v[90:91], v[240:241]
	s_nop 1
	v_permlane16_swap_b32_e32 v234, v238
	v_permlane16_swap_b32_e32 v235, v239
	v_permlane16_swap_b32_e32 v236, v240
	v_permlane16_swap_b32_e32 v237, v241
	v_permlane32_swap_b32_e32 v234, v238
	v_permlane32_swap_b32_e32 v235, v239
	v_permlane32_swap_b32_e32 v236, v240
	v_permlane32_swap_b32_e32 v237, v241
	global_store_dwordx4 v[232:233], v[234:237], off nt
	global_store_dwordx4 v[232:233], v[238:241], off offset:64 nt
	s_waitcnt vmcnt(20)
	v_lshlrev_b32_e32 v244, 16, v186
	v_and_b32_e32 v245, 0xffff0000, v186
	v_lshlrev_b32_e32 v246, 16, v187
	v_and_b32_e32 v247, 0xffff0000, v187
	v_lshlrev_b32_e32 v248, 16, v188
	v_and_b32_e32 v249, 0xffff0000, v188
	v_lshlrev_b32_e32 v250, 16, v189
	v_and_b32_e32 v251, 0xffff0000, v189
	v_pk_add_f32 v[244:245], v[84:85], v[244:245]
	v_pk_add_f32 v[248:249], v[80:81], v[248:249]
	v_pk_add_f32 v[246:247], v[86:87], v[246:247]
	v_pk_add_f32 v[250:251], v[82:83], v[250:251]
	s_nop 1
	v_permlane16_swap_b32_e32 v244, v248
	v_permlane16_swap_b32_e32 v245, v249
	v_permlane16_swap_b32_e32 v246, v250
	v_permlane16_swap_b32_e32 v247, v251
	v_permlane32_swap_b32_e32 v244, v248
	v_permlane32_swap_b32_e32 v245, v249
	v_permlane32_swap_b32_e32 v246, v250
	v_permlane32_swap_b32_e32 v247, v251
	global_store_dwordx4 v[232:233], v[244:247], off offset:512 nt
	global_store_dwordx4 v[232:233], v[248:251], off offset:576 nt
	v_lshl_add_u64 v[232:233], v[232:233], 0, s[56:57]
	s_waitcnt vmcnt(21)
	v_lshlrev_b32_e32 v234, 16, v190
	v_and_b32_e32 v235, 0xffff0000, v190
	v_lshlrev_b32_e32 v236, 16, v191
	v_and_b32_e32 v237, 0xffff0000, v191
	v_lshlrev_b32_e32 v238, 16, v192
	v_and_b32_e32 v239, 0xffff0000, v192
	v_lshlrev_b32_e32 v240, 16, v193
	v_and_b32_e32 v241, 0xffff0000, v193
	v_pk_add_f32 v[234:235], v[76:77], v[234:235]
	v_pk_add_f32 v[238:239], v[72:73], v[238:239]
	v_pk_add_f32 v[236:237], v[78:79], v[236:237]
	v_pk_add_f32 v[240:241], v[74:75], v[240:241]
	s_nop 1
	v_permlane16_swap_b32_e32 v234, v238
	v_permlane16_swap_b32_e32 v235, v239
	v_permlane16_swap_b32_e32 v236, v240
	v_permlane16_swap_b32_e32 v237, v241
	v_permlane32_swap_b32_e32 v234, v238
	v_permlane32_swap_b32_e32 v235, v239
	v_permlane32_swap_b32_e32 v236, v240
	v_permlane32_swap_b32_e32 v237, v241
	global_store_dwordx4 v[232:233], v[234:237], off nt
	global_store_dwordx4 v[232:233], v[238:241], off offset:64 nt
	s_waitcnt vmcnt(22)
	v_lshlrev_b32_e32 v244, 16, v194
	v_and_b32_e32 v245, 0xffff0000, v194
	v_lshlrev_b32_e32 v246, 16, v195
	v_and_b32_e32 v247, 0xffff0000, v195
	v_lshlrev_b32_e32 v248, 16, v196
	v_and_b32_e32 v249, 0xffff0000, v196
	v_lshlrev_b32_e32 v250, 16, v197
	v_and_b32_e32 v251, 0xffff0000, v197
	v_pk_add_f32 v[244:245], v[68:69], v[244:245]
	v_pk_add_f32 v[248:249], v[64:65], v[248:249]
	v_pk_add_f32 v[246:247], v[70:71], v[246:247]
	v_pk_add_f32 v[250:251], v[66:67], v[250:251]
	s_nop 1
	v_permlane16_swap_b32_e32 v244, v248
	v_permlane16_swap_b32_e32 v245, v249
	v_permlane16_swap_b32_e32 v246, v250
	v_permlane16_swap_b32_e32 v247, v251
	v_permlane32_swap_b32_e32 v244, v248
	v_permlane32_swap_b32_e32 v245, v249
	v_permlane32_swap_b32_e32 v246, v250
	v_permlane32_swap_b32_e32 v247, v251
	global_store_dwordx4 v[232:233], v[244:247], off offset:512 nt
	global_store_dwordx4 v[232:233], v[248:251], off offset:576 nt
	v_lshl_add_u64 v[232:233], v[232:233], 0, s[58:59]
	s_waitcnt vmcnt(23)
	v_lshlrev_b32_e32 v234, 16, v198
	v_and_b32_e32 v235, 0xffff0000, v198
	v_lshlrev_b32_e32 v236, 16, v199
	v_and_b32_e32 v237, 0xffff0000, v199
	v_lshlrev_b32_e32 v238, 16, v200
	v_and_b32_e32 v239, 0xffff0000, v200
	v_lshlrev_b32_e32 v240, 16, v201
	v_and_b32_e32 v241, 0xffff0000, v201
	v_pk_add_f32 v[234:235], v[60:61], v[234:235]
	v_pk_add_f32 v[238:239], v[56:57], v[238:239]
	v_pk_add_f32 v[236:237], v[62:63], v[236:237]
	v_pk_add_f32 v[240:241], v[58:59], v[240:241]
	s_nop 1
	v_permlane16_swap_b32_e32 v234, v238
	v_permlane16_swap_b32_e32 v235, v239
	v_permlane16_swap_b32_e32 v236, v240
	v_permlane16_swap_b32_e32 v237, v241
	v_permlane32_swap_b32_e32 v234, v238
	v_permlane32_swap_b32_e32 v235, v239
	v_permlane32_swap_b32_e32 v236, v240
	v_permlane32_swap_b32_e32 v237, v241
	global_store_dwordx4 v[232:233], v[234:237], off nt
	global_store_dwordx4 v[232:233], v[238:241], off offset:64 nt
	s_waitcnt vmcnt(24)
	v_lshlrev_b32_e32 v244, 16, v202
	v_and_b32_e32 v245, 0xffff0000, v202
	v_lshlrev_b32_e32 v246, 16, v203
	v_and_b32_e32 v247, 0xffff0000, v203
	v_lshlrev_b32_e32 v248, 16, v204
	v_and_b32_e32 v249, 0xffff0000, v204
	v_lshlrev_b32_e32 v250, 16, v205
	v_and_b32_e32 v251, 0xffff0000, v205
	v_pk_add_f32 v[244:245], v[52:53], v[244:245]
	v_pk_add_f32 v[248:249], v[48:49], v[248:249]
	v_pk_add_f32 v[246:247], v[54:55], v[246:247]
	v_pk_add_f32 v[250:251], v[50:51], v[250:251]
	s_nop 1
	v_permlane16_swap_b32_e32 v244, v248
	v_permlane16_swap_b32_e32 v245, v249
	v_permlane16_swap_b32_e32 v246, v250
	v_permlane16_swap_b32_e32 v247, v251
	v_permlane32_swap_b32_e32 v244, v248
	v_permlane32_swap_b32_e32 v245, v249
	v_permlane32_swap_b32_e32 v246, v250
	v_permlane32_swap_b32_e32 v247, v251
	global_store_dwordx4 v[232:233], v[244:247], off offset:512 nt
	global_store_dwordx4 v[232:233], v[248:251], off offset:576 nt
	v_lshl_add_u64 v[232:233], v[232:233], 0, s[56:57]
	s_waitcnt vmcnt(25)
	v_lshlrev_b32_e32 v234, 16, v206
	v_and_b32_e32 v235, 0xffff0000, v206
	v_lshlrev_b32_e32 v236, 16, v207
	v_and_b32_e32 v237, 0xffff0000, v207
	v_lshlrev_b32_e32 v238, 16, v208
	v_and_b32_e32 v239, 0xffff0000, v208
	v_lshlrev_b32_e32 v240, 16, v209
	v_and_b32_e32 v241, 0xffff0000, v209
	v_pk_add_f32 v[234:235], v[44:45], v[234:235]
	v_pk_add_f32 v[238:239], v[40:41], v[238:239]
	v_pk_add_f32 v[236:237], v[46:47], v[236:237]
	v_pk_add_f32 v[240:241], v[42:43], v[240:241]
	s_nop 1
	v_permlane16_swap_b32_e32 v234, v238
	v_permlane16_swap_b32_e32 v235, v239
	v_permlane16_swap_b32_e32 v236, v240
	v_permlane16_swap_b32_e32 v237, v241
	v_permlane32_swap_b32_e32 v234, v238
	v_permlane32_swap_b32_e32 v235, v239
	v_permlane32_swap_b32_e32 v236, v240
	v_permlane32_swap_b32_e32 v237, v241
	global_store_dwordx4 v[232:233], v[234:237], off nt
	global_store_dwordx4 v[232:233], v[238:241], off offset:64 nt
	s_waitcnt vmcnt(26)
	v_lshlrev_b32_e32 v244, 16, v210
	v_and_b32_e32 v245, 0xffff0000, v210
	v_lshlrev_b32_e32 v246, 16, v211
	v_and_b32_e32 v247, 0xffff0000, v211
	v_lshlrev_b32_e32 v248, 16, v212
	v_and_b32_e32 v249, 0xffff0000, v212
	v_lshlrev_b32_e32 v250, 16, v213
	v_and_b32_e32 v251, 0xffff0000, v213
	v_pk_add_f32 v[244:245], v[36:37], v[244:245]
	v_pk_add_f32 v[248:249], v[32:33], v[248:249]
	v_pk_add_f32 v[246:247], v[38:39], v[246:247]
	v_pk_add_f32 v[250:251], v[34:35], v[250:251]
	s_nop 1
	v_permlane16_swap_b32_e32 v244, v248
	v_permlane16_swap_b32_e32 v245, v249
	v_permlane16_swap_b32_e32 v246, v250
	v_permlane16_swap_b32_e32 v247, v251
	v_permlane32_swap_b32_e32 v244, v248
	v_permlane32_swap_b32_e32 v245, v249
	v_permlane32_swap_b32_e32 v246, v250
	v_permlane32_swap_b32_e32 v247, v251
	global_store_dwordx4 v[232:233], v[244:247], off offset:512 nt
	global_store_dwordx4 v[232:233], v[248:251], off offset:576 nt
	v_lshl_add_u64 v[232:233], v[232:233], 0, s[56:57]
	s_waitcnt vmcnt(27)
	v_lshlrev_b32_e32 v234, 16, v214
	v_and_b32_e32 v235, 0xffff0000, v214
	v_lshlrev_b32_e32 v236, 16, v215
	v_and_b32_e32 v237, 0xffff0000, v215
	v_lshlrev_b32_e32 v238, 16, v216
	v_and_b32_e32 v239, 0xffff0000, v216
	v_lshlrev_b32_e32 v240, 16, v217
	v_and_b32_e32 v241, 0xffff0000, v217
	v_pk_add_f32 v[234:235], v[28:29], v[234:235]
	v_pk_add_f32 v[238:239], v[24:25], v[238:239]
	v_pk_add_f32 v[236:237], v[30:31], v[236:237]
	v_pk_add_f32 v[240:241], v[26:27], v[240:241]
	s_nop 1
	v_permlane16_swap_b32_e32 v234, v238
	v_permlane16_swap_b32_e32 v235, v239
	v_permlane16_swap_b32_e32 v236, v240
	v_permlane16_swap_b32_e32 v237, v241
	v_permlane32_swap_b32_e32 v234, v238
	v_permlane32_swap_b32_e32 v235, v239
	v_permlane32_swap_b32_e32 v236, v240
	v_permlane32_swap_b32_e32 v237, v241
	global_store_dwordx4 v[232:233], v[234:237], off nt
	global_store_dwordx4 v[232:233], v[238:241], off offset:64 nt
	s_waitcnt vmcnt(28)
	v_lshlrev_b32_e32 v244, 16, v218
	v_and_b32_e32 v245, 0xffff0000, v218
	v_lshlrev_b32_e32 v246, 16, v219
	v_and_b32_e32 v247, 0xffff0000, v219
	v_lshlrev_b32_e32 v248, 16, v220
	v_and_b32_e32 v249, 0xffff0000, v220
	v_lshlrev_b32_e32 v250, 16, v221
	v_and_b32_e32 v251, 0xffff0000, v221
	v_pk_add_f32 v[244:245], v[20:21], v[244:245]
	v_pk_add_f32 v[248:249], v[16:17], v[248:249]
	v_pk_add_f32 v[246:247], v[22:23], v[246:247]
	v_pk_add_f32 v[250:251], v[18:19], v[250:251]
	s_nop 1
	v_permlane16_swap_b32_e32 v244, v248
	v_permlane16_swap_b32_e32 v245, v249
	v_permlane16_swap_b32_e32 v246, v250
	v_permlane16_swap_b32_e32 v247, v251
	v_permlane32_swap_b32_e32 v244, v248
	v_permlane32_swap_b32_e32 v245, v249
	v_permlane32_swap_b32_e32 v246, v250
	v_permlane32_swap_b32_e32 v247, v251
	global_store_dwordx4 v[232:233], v[244:247], off offset:512 nt
	global_store_dwordx4 v[232:233], v[248:251], off offset:576 nt
	v_lshl_add_u64 v[232:233], v[232:233], 0, s[56:57]
	s_waitcnt vmcnt(29)
	v_lshlrev_b32_e32 v234, 16, v222
	v_and_b32_e32 v235, 0xffff0000, v222
	v_lshlrev_b32_e32 v236, 16, v223
	v_and_b32_e32 v237, 0xffff0000, v223
	v_lshlrev_b32_e32 v238, 16, v224
	v_and_b32_e32 v239, 0xffff0000, v224
	v_lshlrev_b32_e32 v240, 16, v225
	v_and_b32_e32 v241, 0xffff0000, v225
	v_pk_add_f32 v[234:235], v[12:13], v[234:235]
	v_pk_add_f32 v[238:239], v[8:9], v[238:239]
	v_pk_add_f32 v[236:237], v[14:15], v[236:237]
	v_pk_add_f32 v[240:241], v[10:11], v[240:241]
	s_nop 1
	v_permlane16_swap_b32_e32 v234, v238
	v_permlane16_swap_b32_e32 v235, v239
	v_permlane16_swap_b32_e32 v236, v240
	v_permlane16_swap_b32_e32 v237, v241
	v_permlane32_swap_b32_e32 v234, v238
	v_permlane32_swap_b32_e32 v235, v239
	v_permlane32_swap_b32_e32 v236, v240
	v_permlane32_swap_b32_e32 v237, v241
	global_store_dwordx4 v[232:233], v[234:237], off nt
	global_store_dwordx4 v[232:233], v[238:241], off offset:64 nt
	s_waitcnt vmcnt(30)
	v_lshlrev_b32_e32 v244, 16, v226
	v_and_b32_e32 v245, 0xffff0000, v226
	v_lshlrev_b32_e32 v246, 16, v227
	v_and_b32_e32 v247, 0xffff0000, v227
	v_lshlrev_b32_e32 v248, 16, v228
	v_and_b32_e32 v249, 0xffff0000, v228
	v_lshlrev_b32_e32 v250, 16, v229
	v_and_b32_e32 v251, 0xffff0000, v229
	v_pk_add_f32 v[244:245], v[4:5], v[244:245]
	v_pk_add_f32 v[248:249], v[0:1], v[248:249]
	v_pk_add_f32 v[246:247], v[6:7], v[246:247]
	v_pk_add_f32 v[250:251], v[2:3], v[250:251]
	s_nop 1
	v_permlane16_swap_b32_e32 v244, v248
	v_permlane16_swap_b32_e32 v245, v249
	v_permlane16_swap_b32_e32 v246, v250
	v_permlane16_swap_b32_e32 v247, v251
	v_permlane32_swap_b32_e32 v244, v248
	v_permlane32_swap_b32_e32 v245, v249
	v_permlane32_swap_b32_e32 v246, v250
	v_permlane32_swap_b32_e32 v247, v251
	global_store_dwordx4 v[232:233], v[244:247], off offset:512 nt
	global_store_dwordx4 v[232:233], v[248:251], off offset:576 nt
	s_cbranch_vccnz .LBB0_1460
	s_andn2_b64 vcc, exec, s[2:3]
	s_cbranch_vccnz .LBB0_1459
	s_barrier
	s_branch .LBB0_1459
